# NA unit setup: full wait after the bias-table pointer load moved behind the next two tile loads so all five loads overlap
# speedup vs baseline: 1.0058x; 1.0019x over previous
.LBB0_651:
	v_mov_b32_e32 v2, s64
	v_mov_b32_e32 v3, s65
	v_mov_b32_e32 v4, s64
	v_readfirstlane_b32 s6, v2
	v_readfirstlane_b32 s7, v3
	v_mov_b32_e32 v5, s65
	v_mov_b32_e32 v2, s6
	v_mov_b32_e32 v3, s7
	global_load_dwordx2 v[2:3], v[2:3], off offset:248
	s_waitcnt vmcnt(0) lgkmcnt(0)
	v_mov_b32_e32 v71, v1
	v_readfirstlane_b32 s6, v4
	v_readfirstlane_b32 s7, v5
	v_readfirstlane_b32 s8, v2
	v_mov_b32_e32 v4, s6
	v_mov_b32_e32 v5, s7
	v_mov_b32_e32 v10, v2
	v_mov_b32_e32 v11, v3
	v_mov_b32_e32 v4, s64
	v_mov_b32_e32 v5, s65
	s_waitcnt vmcnt(0) lgkmcnt(0)
	v_readfirstlane_b32 s9, v3
	v_readfirstlane_b32 s6, v4
	v_readfirstlane_b32 s7, v5
	v_mov_b32_e32 v0, s64
	v_mov_b32_e32 v4, s6
	s_add_i32 s6, s4, 0xfffffe00
	v_mov_b32_e32 v5, s7
	s_add_u32 s14, s8, 0x9f00000
	v_mov_b32_e32 v12, v2
	v_mov_b32_e32 v13, v3
	v_mov_b32_e32 v4, v247
	s_addc_u32 s15, s9, 0
	s_lshr_b32 s12, s6, 6
	s_lshl_b32 s6, s6, 1
	s_and_b32 s23, s6, 30
	s_waitcnt vmcnt(0) lgkmcnt(0)
	s_mov_b32 s7, s19
	v_ashrrev_i32_e32 v5, 8, v4
	v_lshrrev_b32_e32 v14, 1, v4
	v_add_u32_e32 v8, s23, v5
	v_and_b32_e32 v15, 24, v14
	v_lshlrev_b32_e32 v14, 6, v8
	s_lshl_b32 s6, s12, 11
	v_lshrrev_b32_e32 v9, 2, v4
	v_lshlrev_b32_e32 v70, 1, v15
	v_ashrrev_i32_e32 v15, 31, v14
	v_and_b32_e32 v6, 15, v4
	v_and_b32_e32 v7, 48, v9
	v_lshl_add_u64 v[68:69], v[14:15], 0, s[6:7]
	v_mov_b64_e32 v[2:3], s[14:15]
	v_or3_b32 v68, v68, v7, v6
	s_bfe_u32 s22, s4, 0x20004
	v_mad_u64_u32 v[14:15], s[8:9], v68, s2, v[2:3]
	s_lshl_b32 s18, s22, 7
	v_mad_i32_i24 v15, v69, s2, v15
	v_lshl_add_u64 v[14:15], v[14:15], 0, s[18:19]
	v_mov_b32_e32 v16, s65
	v_lshl_add_u64 v[14:15], v[14:15], 0, v[70:71]
	global_load_dwordx4 v[20:23], v[14:15], off offset:768
	global_load_dwordx4 v[24:27], v[14:15], off offset:832
	v_ashrrev_i32_e32 v72, 3, v4
	v_readfirstlane_b32 s7, v0
	v_readfirstlane_b32 s8, v16
	s_mov_b32 s9, s19
	v_mov_b32_e32 v14, s7
	v_mov_b32_e32 v15, s8
	s_lshl_b32 s7, s22, 6
	s_lshl_b32 s8, s12, 8
	s_add_i32 s12, s7, 0x80
	s_addk_i32 s8, 0x4000
	v_readfirstlane_b32 s13, v10
	v_readfirstlane_b32 s24, v11
	v_ashrrev_i32_e32 v73, 31, v72
	v_mov_b32_e32 v10, s13
	v_mov_b32_e32 v11, s24
	v_add_u32_e32 v18, s12, v72
	v_lshl_add_u64 v[16:17], v[72:73], 0, s[8:9]
	s_mov_b32 s9, 0x9000
	v_lshlrev_b32_e32 v36, 3, v4
	v_mad_i64_i32 v[10:11], s[12:13], v18, s9, v[10:11]
	v_mad_u64_u32 v[18:19], s[12:13], v16, s2, v[2:3]
	v_and_b32_e32 v71, 56, v36
	s_mov_b64 s[12:13], 0x17700000
	v_mad_i32_i24 v19, v17, s2, v19
	v_lshlrev_b32_e32 v0, 1, v71
	v_lshl_add_u64 v[2:3], v[10:11], 0, s[12:13]
	v_lshl_add_u64 v[10:11], v[18:19], 0, s[18:19]
	s_lshl_b32 s18, s8, 1
	global_load_dwordx2 v[14:15], v[14:15], off offset:112
	v_lshl_add_u64 v[10:11], v[10:11], 0, v[0:1]
	v_lshl_add_u64 v[16:17], v[2:3], 0, s[18:19]
	v_lshl_add_u64 v[16:17], v[16:17], 0, v[0:1]
	global_load_dwordx4 v[28:31], v[10:11], off offset:1280
	global_load_dwordx4 v[32:35], v[16:17], off
	s_waitcnt vmcnt(0) lgkmcnt(0)
	v_sub_u32_e64 v10, s23, 4 clamp
	v_sub_u32_e64 v11, s23, 3 clamp
	v_readfirstlane_b32 s8, v10
	v_readfirstlane_b32 s9, v11
	s_min_u32 s8, s8, 24
	s_min_u32 s9, s9, 24
	v_lshlrev_b32_e32 v10, 4, v4
	v_lshlrev_b32_e32 v11, 1, v4
	s_movk_i32 s18, 0x90
	s_sub_i32 s51, s9, s8
	v_readfirstlane_b32 s8, v12
	v_readfirstlane_b32 s9, v13
	v_and_b32_e32 v12, 32, v36
	v_and_b32_e32 v10, 16, v10
	v_and_b32_e32 v11, 4, v11
	v_mul_lo_u32 v13, v72, s18
	s_add_i32 s51, s51, 8
	v_or3_b32 v96, v12, v10, v11
	v_add_u32_e32 v97, 16, v13
	s_mov_b64 s[12:13], -1
	v_add_u32_e32 v10, v97, v0
	v_lshl_add_u32 v11, v96, 1, v97
	s_cmp_gt_i32 s51, -4
	v_readfirstlane_b32 s18, v14
	v_readfirstlane_b32 s23, v15
	v_and_b32_e32 v98, 12, v9
	v_add_u32_e32 v11, 0x2000, v11
	s_waitcnt vmcnt(0) lgkmcnt(0)
	ds_write_b128 v10, v[28:31]
	ds_write2_b64 v11, v[32:33], v[34:35] offset0:128 offset1:130
	s_waitcnt lgkmcnt(0)
	s_barrier
	s_cbranch_scc1 .LBB0_653
	v_and_b32_e32 v36, 12, v9
	s_mov_b64 s[12:13], 0
